# diff tile loop: removed 15 dead s_mov per tile (SGPR zero tuple no longer used since the MFMA C operand became inline 0)
# baseline (speedup 1.0000x reference)
.LBB0_1749:
	s_sub_i32 s0, s14, 63
	v_cmp_le_i32_e32 vcc, s0, v174
	s_and_saveexec_b64 s[6:7], vcc
	s_cbranch_execz .LBB0_1746
	v_cmp_gt_i32_e32 vcc, s14, v172
	s_waitcnt lgkmcnt(7)
	v_mfma_f32_32x32x16_bf16 v[114:129], v[82:85], v[130:133], 0
	s_waitcnt lgkmcnt(6)
	v_mfma_f32_32x32x16_bf16 v[98:113], v[86:89], v[130:133], 0
	s_waitcnt lgkmcnt(5)
	v_mfma_f32_32x32x16_bf16 v[114:129], v[90:93], v[134:137], v[114:129]
	s_waitcnt lgkmcnt(4)
	v_mfma_f32_32x32x16_bf16 v[98:113], v[94:97], v[134:137], v[98:113]
	s_and_saveexec_b64 s[8:9], vcc
	s_cbranch_execz .LBB0_1752
	v_add_u32_e32 v70, s14, v157
	v_subrev_u32_e32 v205, 63, v70
	v_subrev_u32_e32 v211, 31, v70
	v_subrev_u32_e32 v210, 30, v70
	v_subrev_u32_e32 v209, 61, v70
	v_subrev_u32_e32 v208, 29, v70
	v_subrev_u32_e32 v207, 60, v70
	v_subrev_u32_e32 v206, 28, v70
	v_subrev_u32_e32 v204, 55, v70
	v_subrev_u32_e32 v203, 23, v70
	v_subrev_u32_e32 v202, 54, v70
	v_subrev_u32_e32 v201, 22, v70
	v_subrev_u32_e32 v200, 53, v70
	v_subrev_u32_e32 v199, 21, v70
	v_subrev_u32_e32 v198, 52, v70
	v_subrev_u32_e32 v197, 20, v70
	v_subrev_u32_e32 v196, 47, v70
	v_add_u32_e32 v195, -15, v70
	v_subrev_u32_e32 v194, 46, v70
	v_add_u32_e32 v193, -14, v70
	v_subrev_u32_e32 v192, 45, v70
	v_add_u32_e32 v191, -13, v70
	v_subrev_u32_e32 v190, 44, v70
	v_add_u32_e32 v171, -12, v70
	v_subrev_u32_e32 v170, 39, v70
	v_add_u32_e32 v169, -7, v70
	v_subrev_u32_e32 v168, 38, v70
	v_add_u32_e32 v167, -6, v70
	v_subrev_u32_e32 v166, 37, v70
	v_add_u32_e32 v165, -5, v70
	v_subrev_u32_e32 v164, 36, v70
	v_add_u32_e32 v162, -4, v70
	v_cmp_le_i32_e64 s[0:1], v211, v156
	s_nop 1
	v_cndmask_b32_e64 v98, v236, v98, s[0:1]
	v_cmp_lt_i32_e64 s[0:1], v205, v156
	s_nop 1
	v_cndmask_b32_e64 v115, v236, v115, s[0:1]
	v_cmp_le_i32_e64 s[0:1], v205, v156
	s_nop 1
	v_cndmask_b32_e64 v114, v236, v114, s[0:1]
	v_cmp_le_i32_e64 s[0:1], v210, v156
	s_nop 1
	v_cndmask_b32_e64 v99, v236, v99, s[0:1]
	v_cmp_le_i32_e64 s[0:1], v209, v156
	s_nop 1
	v_cndmask_b32_e64 v116, v236, v116, s[0:1]
	v_cmp_le_i32_e64 s[0:1], v208, v156
	s_nop 1
	v_cndmask_b32_e64 v100, v236, v100, s[0:1]
	v_cmp_le_i32_e64 s[0:1], v207, v156
	s_nop 1
	v_cndmask_b32_e64 v117, v236, v117, s[0:1]
	v_cmp_le_i32_e64 s[0:1], v206, v156
	s_nop 1
	v_cndmask_b32_e64 v101, v236, v101, s[0:1]
	v_cmp_le_i32_e64 s[0:1], v204, v156
	s_nop 1
	v_cndmask_b32_e64 v118, v236, v118, s[0:1]
	v_cmp_le_i32_e64 s[0:1], v203, v156
	s_nop 1
	v_cndmask_b32_e64 v102, v236, v102, s[0:1]
	v_cmp_le_i32_e64 s[0:1], v202, v156
	s_nop 1
	v_cndmask_b32_e64 v119, v236, v119, s[0:1]
	v_cmp_le_i32_e64 s[0:1], v201, v156
	s_nop 1
	v_cndmask_b32_e64 v103, v236, v103, s[0:1]
	v_cmp_le_i32_e64 s[0:1], v200, v156
	s_nop 1
	v_cndmask_b32_e64 v120, v236, v120, s[0:1]
	v_cmp_le_i32_e64 s[0:1], v199, v156
	s_nop 1
	v_cndmask_b32_e64 v104, v236, v104, s[0:1]
	v_cmp_le_i32_e64 s[0:1], v198, v156
	s_nop 1
	v_cndmask_b32_e64 v121, v236, v121, s[0:1]
	v_cmp_le_i32_e64 s[0:1], v197, v156
	s_nop 1
	v_cndmask_b32_e64 v105, v236, v105, s[0:1]
	v_cmp_le_i32_e64 s[0:1], v196, v156
	s_nop 1
	v_cndmask_b32_e64 v122, v236, v122, s[0:1]
	v_cmp_le_i32_e64 s[0:1], v195, v156
	s_nop 1
	v_cndmask_b32_e64 v106, v236, v106, s[0:1]
	v_cmp_le_i32_e64 s[0:1], v194, v156
	s_nop 1
	v_cndmask_b32_e64 v123, v236, v123, s[0:1]
	v_cmp_le_i32_e64 s[0:1], v193, v156
	s_nop 1
	v_cndmask_b32_e64 v107, v236, v107, s[0:1]
	v_cmp_le_i32_e64 s[0:1], v192, v156
	s_nop 1
	v_cndmask_b32_e64 v124, v236, v124, s[0:1]
	v_cmp_le_i32_e64 s[0:1], v191, v156
	s_nop 1
	v_cndmask_b32_e64 v108, v236, v108, s[0:1]
	v_cmp_le_i32_e64 s[0:1], v190, v156
	s_nop 1
	v_cndmask_b32_e64 v125, v236, v125, s[0:1]
	v_cmp_le_i32_e64 s[0:1], v171, v156
	s_nop 1
	v_cndmask_b32_e64 v109, v236, v109, s[0:1]
	v_cmp_le_i32_e64 s[0:1], v170, v156
	s_nop 1
	v_cndmask_b32_e64 v126, v236, v126, s[0:1]
	v_cmp_le_i32_e64 s[0:1], v169, v156
	s_nop 1
	v_cndmask_b32_e64 v110, v236, v110, s[0:1]
	v_cmp_le_i32_e64 s[0:1], v168, v156
	s_nop 1
	v_cndmask_b32_e64 v127, v236, v127, s[0:1]
	v_cmp_le_i32_e64 s[0:1], v167, v156
	s_nop 1
	v_cndmask_b32_e64 v111, v236, v111, s[0:1]
	v_cmp_le_i32_e64 s[0:1], v166, v156
	s_nop 1
	v_cndmask_b32_e64 v128, v236, v128, s[0:1]
	v_cmp_le_i32_e64 s[0:1], v165, v156
	s_nop 1
	v_cndmask_b32_e64 v112, v236, v112, s[0:1]
	v_cmp_le_i32_e64 s[0:1], v164, v156
	s_nop 1
	v_cndmask_b32_e64 v129, v236, v129, s[0:1]
	v_cmp_le_i32_e64 s[0:1], v162, v156
	s_nop 1
	v_cndmask_b32_e64 v113, v236, v113, s[0:1]
